# barrier wait loops poll the arrival counter with s_sleep 4 instead of s_sleep 1 (less traffic on the hot word); otherwise as the widened-gate-load version
# speedup vs baseline: 1.0013x; 1.0013x over previous
.LBB0_134:
	s_and_b32 s2, s0, 0xff
	s_mov_b64 s[36:37], -1
	s_cmp_lg_u32 s2, 0
	s_mov_b64 s[42:43], -1
	s_sleep 4
	s_cbranch_scc1 .LBB0_137
	v_readlane_b32 s14, v251, 4
	v_readlane_b32 s15, v251, 5
	s_nop 4
	global_load_dword v2, v1, s[14:15] sc1
	s_waitcnt vmcnt(0)
	v_cmp_eq_u32_e32 vcc, 0, v2
	s_cbranch_vccnz .LBB0_139
	s_mov_b64 s[42:43], 0
	s_mov_b64 s[38:39], -1

.LBB0_520:
	s_and_b32 s2, s0, 0xff
	s_mov_b64 s[36:37], -1
	s_cmp_lg_u32 s2, 0
	s_mov_b64 s[44:45], -1
	s_sleep 4
	s_cbranch_scc1 .LBB0_523
	v_readlane_b32 s14, v251, 4
	v_readlane_b32 s15, v251, 5
	s_nop 4
	global_load_dword v2, v1, s[14:15] sc1
	s_waitcnt vmcnt(0)
	v_cmp_eq_u32_e32 vcc, 0, v2
	s_cbranch_vccnz .LBB0_525
	s_mov_b64 s[44:45], 0
	s_mov_b64 s[38:39], -1
